# P1/P8 last unit: the no-next-unit prefetch DMAs re-read the unit's last two K-tiles (L2-resident) instead of its first two (displaced), to unload the phase-end drain; stacked on v93
# speedup vs baseline: 1.0038x; 1.0038x over previous
.LBB0_200:
	s_add_u32 s46, s6, 0x200
	s_addc_u32 s47, s7, 0
	s_ashr_i32 s91, s90, 31
	s_lshl_b64 s[2:3], s[90:91], 19
	v_readlane_b32 s8, v254, 62
	v_readlane_b32 s9, v254, 63
	s_add_u32 s94, s8, s2
	s_addc_u32 s95, s9, s3
	s_and_b64 s[2:3], s[0:1], exec
	s_cselect_b32 s48, s95, s25
	s_cselect_b32 s49, s94, s24
	s_ashr_i32 s89, s88, 31
	s_lshl_b64 s[2:3], s[88:89], 19
	s_add_u32 s92, s68, s2
	s_addc_u32 s93, s69, s3
	s_and_b64 s[2:3], s[0:1], exec
	s_cselect_b32 s89, s93, s7
	s_cselect_b32 s91, s92, s6
	s_and_b64 s[2:3], s[0:1], exec
	s_cselect_b32 s2, 0, 0x700
	s_add_u32 s49, s49, s2
	s_addc_u32 s48, s48, 0
	s_add_u32 s91, s91, s2
	s_addc_u32 s89, s89, 0
	v_lshl_add_u64 v[140:141], s[24:25], 0, v[130:131]
	s_add_i32 vcc_lo, s11, 0xc000
	v_lshl_add_u64 v[66:67], v[140:141], 0, s[42:43]
	s_mov_b32 m0, vcc_lo
	s_add_i32 vcc_hi, s11, 0xe000
	global_load_lds_dwordx4 v[66:67], off
	v_lshl_add_u64 v[66:67], v[140:141], 0, s[44:45]
	s_mov_b32 m0, vcc_hi
	s_nop 0
	global_load_lds_dwordx4 v[66:67], off
	s_waitcnt vmcnt(8)
	s_waitcnt lgkmcnt(0)
	s_waitcnt lgkmcnt(0)
	v_mfma_f32_16x16x32_bf16 v[86:89], v[10:13], v[50:53], 0
	v_mfma_f32_16x16x32_bf16 v[90:93], v[14:17], v[54:57], v[86:89]
	s_barrier
	s_setprio 1
	v_mfma_f32_16x16x32_bf16 v[86:89], v[2:5], v[58:61], 0
	v_mfma_f32_16x16x32_bf16 v[66:69], v[2:5], v[34:37], 0
	v_mfma_f32_16x16x32_bf16 v[70:73], v[10:13], v[34:37], 0
	v_mfma_f32_16x16x32_bf16 v[74:77], v[2:5], v[42:45], 0
	v_mfma_f32_16x16x32_bf16 v[78:81], v[10:13], v[42:45], 0
	v_mfma_f32_16x16x32_bf16 v[82:85], v[2:5], v[50:53], 0
	v_mfma_f32_16x16x32_bf16 v[94:97], v[6:9], v[62:65], v[86:89]
	v_mfma_f32_16x16x32_bf16 v[86:89], v[10:13], v[58:61], 0
	v_mfma_f32_16x16x32_bf16 v[66:69], v[6:9], v[38:41], v[66:69]
	v_mfma_f32_16x16x32_bf16 v[70:73], v[14:17], v[38:41], v[70:73]
	v_mfma_f32_16x16x32_bf16 v[74:77], v[6:9], v[46:49], v[74:77]
	v_mfma_f32_16x16x32_bf16 v[78:81], v[14:17], v[46:49], v[78:81]
	v_mfma_f32_16x16x32_bf16 v[82:85], v[6:9], v[54:57], v[82:85]
	v_mfma_f32_16x16x32_bf16 v[106:109], v[14:17], v[62:65], v[86:89]
	s_setprio 0
	s_setprio 1
	v_mfma_f32_16x16x32_bf16 v[86:89], v[18:21], v[34:37], 0
	v_mfma_f32_16x16x32_bf16 v[34:37], v[26:29], v[34:37], 0
	v_mfma_f32_16x16x32_bf16 v[110:113], v[22:25], v[38:41], v[86:89]
	v_mfma_f32_16x16x32_bf16 v[34:37], v[30:33], v[38:41], v[34:37]
	v_mfma_f32_16x16x32_bf16 v[38:41], v[18:21], v[42:45], 0
	v_mfma_f32_16x16x32_bf16 v[42:45], v[26:29], v[42:45], 0
	v_mfma_f32_16x16x32_bf16 v[38:41], v[22:25], v[46:49], v[38:41]
	v_mfma_f32_16x16x32_bf16 v[42:45], v[30:33], v[46:49], v[42:45]
	v_mfma_f32_16x16x32_bf16 v[46:49], v[18:21], v[50:53], 0
	v_mfma_f32_16x16x32_bf16 v[50:53], v[26:29], v[50:53], 0
	v_mfma_f32_16x16x32_bf16 v[46:49], v[22:25], v[54:57], v[46:49]
	v_mfma_f32_16x16x32_bf16 v[50:53], v[30:33], v[54:57], v[50:53]
	v_mfma_f32_16x16x32_bf16 v[54:57], v[18:21], v[58:61], 0
	v_mfma_f32_16x16x32_bf16 v[58:61], v[26:29], v[58:61], 0
	v_mfma_f32_16x16x32_bf16 v[54:57], v[22:25], v[62:65], v[54:57]
	v_mfma_f32_16x16x32_bf16 v[58:61], v[30:33], v[62:65], v[58:61]
	s_setprio 0
	s_barrier
	v_lshl_add_u64 v[184:185], s[6:7], 0, v[132:133]
	s_add_i32 s8, s96, s51
	v_lshl_add_u64 v[150:151], v[184:185], 0, s[64:65]
	s_mov_b32 m0, s8
	s_add_i32 s9, s8, 0x2000
	ds_read_b128 v[62:65], v147 offset:16384
	ds_read_b128 v[86:89], v147 offset:17408
	ds_read_b128 v[98:101], v147 offset:18432
	ds_read_b128 v[102:105], v147 offset:19456
	ds_read_b128 v[114:117], v147 offset:20480
	ds_read_b128 v[118:121], v147 offset:21504
	ds_read_b128 v[122:125], v147 offset:22528
	ds_read_b128 v[126:129], v147 offset:23552
	global_load_lds_dwordx4 v[150:151], off
	v_lshl_add_u64 v[150:151], v[184:185], 0, s[66:67]
	s_mov_b32 m0, s9
	s_add_i32 s33, s97, s51
	global_load_lds_dwordx4 v[150:151], off
	v_lshl_add_u64 v[150:151], v[184:185], 0, s[72:73]
	s_mov_b32 m0, s33
	s_add_i32 s2, s33, 0x2000
	global_load_lds_dwordx4 v[150:151], off
	v_lshl_add_u64 v[150:151], v[184:185], 0, s[74:75]
	s_mov_b32 m0, s2
	s_nop 0
	global_load_lds_dwordx4 v[150:151], off
	v_lshl_add_u64 v[150:151], v[140:141], 0, s[64:65]
	s_mov_b32 m0, s11
	s_nop 0
	global_load_lds_dwordx4 v[150:151], off
	v_lshl_add_u64 v[150:151], v[140:141], 0, s[66:67]
	s_mov_b32 m0, s54
	s_nop 0
	global_load_lds_dwordx4 v[150:151], off
	s_waitcnt vmcnt(8)
	s_waitcnt lgkmcnt(0)
	s_waitcnt lgkmcnt(0)
	v_mfma_f32_16x16x32_bf16 v[150:153], v[2:5], v[62:65], 0
	v_mfma_f32_16x16x32_bf16 v[160:163], v[2:5], v[98:101], 0
	s_barrier
	s_setprio 1
	v_mfma_f32_16x16x32_bf16 v[168:171], v[2:5], v[114:117], 0
	v_mfma_f32_16x16x32_bf16 v[2:5], v[2:5], v[122:125], 0
	v_mfma_f32_16x16x32_bf16 v[152:155], v[6:9], v[86:89], v[150:153]
	v_mfma_f32_16x16x32_bf16 v[160:163], v[6:9], v[102:105], v[160:163]
	v_mfma_f32_16x16x32_bf16 v[168:171], v[6:9], v[118:121], v[168:171]
	v_mfma_f32_16x16x32_bf16 v[2:5], v[6:9], v[126:129], v[2:5]
	v_mfma_f32_16x16x32_bf16 v[6:9], v[10:13], v[122:125], 0
	v_mfma_f32_16x16x32_bf16 v[156:159], v[10:13], v[62:65], 0
	v_mfma_f32_16x16x32_bf16 v[164:167], v[10:13], v[98:101], 0
	v_mfma_f32_16x16x32_bf16 v[172:175], v[10:13], v[114:117], 0
	v_mfma_f32_16x16x32_bf16 v[10:13], v[14:17], v[126:129], v[6:9]
	v_mfma_f32_16x16x32_bf16 v[156:159], v[14:17], v[86:89], v[156:159]
	v_mfma_f32_16x16x32_bf16 v[164:167], v[14:17], v[102:105], v[164:167]
	v_mfma_f32_16x16x32_bf16 v[172:175], v[14:17], v[118:121], v[172:175]
	s_setprio 0
	s_setprio 1
	v_mfma_f32_16x16x32_bf16 v[6:9], v[18:21], v[62:65], 0
	v_mfma_f32_16x16x32_bf16 v[14:17], v[22:25], v[86:89], v[6:9]
	v_mfma_f32_16x16x32_bf16 v[6:9], v[26:29], v[62:65], 0
	v_mfma_f32_16x16x32_bf16 v[176:179], v[30:33], v[86:89], v[6:9]
	v_mfma_f32_16x16x32_bf16 v[6:9], v[18:21], v[98:101], 0
	v_mfma_f32_16x16x32_bf16 v[180:183], v[22:25], v[102:105], v[6:9]
	v_mfma_f32_16x16x32_bf16 v[6:9], v[26:29], v[98:101], 0
	v_mfma_f32_16x16x32_bf16 v[188:191], v[30:33], v[102:105], v[6:9]
	v_mfma_f32_16x16x32_bf16 v[6:9], v[18:21], v[114:117], 0
	v_mfma_f32_16x16x32_bf16 v[192:195], v[22:25], v[118:121], v[6:9]
	v_mfma_f32_16x16x32_bf16 v[6:9], v[26:29], v[114:117], 0
	v_mfma_f32_16x16x32_bf16 v[196:199], v[30:33], v[118:121], v[6:9]
	v_mfma_f32_16x16x32_bf16 v[6:9], v[18:21], v[122:125], 0
	v_mfma_f32_16x16x32_bf16 v[200:203], v[22:25], v[126:129], v[6:9]
	v_mfma_f32_16x16x32_bf16 v[6:9], v[26:29], v[122:125], 0
	v_mfma_f32_16x16x32_bf16 v[204:207], v[30:33], v[126:129], v[6:9]
	s_setprio 0
	s_barrier
	s_add_i32 s3, 0, 0x18000
	s_add_i32 s35, 0, 0x1c000
	v_add_u32_e32 v149, s3, v144
	v_add_u32_e32 v150, s35, v144
	s_nop 0
	ds_read_b128 v[6:9], v149
	ds_read_b128 v[26:29], v149 offset:1024
	ds_read_b128 v[30:33], v149 offset:2048
	ds_read_b128 v[208:211], v149 offset:3072
	ds_read_b128 v[212:215], v150
	ds_read_b128 v[216:219], v150 offset:1024
	ds_read_b128 v[220:223], v150 offset:2048
	ds_read_b128 v[224:227], v150 offset:3072
	s_mov_b32 m0, s55
	v_lshl_add_u64 v[62:63], v[140:141], 0, s[72:73]
	ds_read_b128 v[18:21], v147 offset:32768
	ds_read_b128 v[22:25], v147 offset:33792
	ds_read_b128 v[228:231], v147 offset:34816
	ds_read_b128 v[232:235], v147 offset:35840
	ds_read_b128 v[236:239], v147 offset:36864
	ds_read_b128 v[240:243], v147 offset:37888
	ds_read_b128 v[244:247], v147 offset:38912
	ds_read_b128 v[248:251], v147 offset:39936
	global_load_lds_dwordx4 v[62:63], off
	v_lshl_add_u64 v[62:63], v[140:141], 0, s[74:75]
	s_mov_b32 m0, s56
	s_nop 0
	global_load_lds_dwordx4 v[62:63], off
	s_waitcnt vmcnt(8)
	s_waitcnt lgkmcnt(0)
	s_waitcnt lgkmcnt(0)
	v_mfma_f32_16x16x32_bf16 v[62:65], v[6:9], v[18:21], v[66:69]
	v_mfma_f32_16x16x32_bf16 v[118:121], v[26:29], v[22:25], v[62:65]
	s_barrier
	s_setprio 1
	v_mfma_f32_16x16x32_bf16 v[62:65], v[30:33], v[18:21], v[70:73]
	v_mfma_f32_16x16x32_bf16 v[114:117], v[208:211], v[22:25], v[62:65]
	v_mfma_f32_16x16x32_bf16 v[62:65], v[6:9], v[228:231], v[74:77]
	v_mfma_f32_16x16x32_bf16 v[102:105], v[26:29], v[232:235], v[62:65]
	v_mfma_f32_16x16x32_bf16 v[62:65], v[30:33], v[228:231], v[78:81]
	v_mfma_f32_16x16x32_bf16 v[98:101], v[208:211], v[232:235], v[62:65]
	v_mfma_f32_16x16x32_bf16 v[62:65], v[6:9], v[236:239], v[82:85]
	v_mfma_f32_16x16x32_bf16 v[86:89], v[26:29], v[240:243], v[62:65]
	v_mfma_f32_16x16x32_bf16 v[62:65], v[30:33], v[236:239], v[90:93]
	v_mfma_f32_16x16x32_bf16 v[82:85], v[208:211], v[240:243], v[62:65]
	v_mfma_f32_16x16x32_bf16 v[62:65], v[6:9], v[244:247], v[94:97]
	v_mfma_f32_16x16x32_bf16 v[70:73], v[26:29], v[248:251], v[62:65]
	v_mfma_f32_16x16x32_bf16 v[62:65], v[30:33], v[244:247], v[106:109]
	v_mfma_f32_16x16x32_bf16 v[62:65], v[208:211], v[248:251], v[62:65]
	s_setprio 0
	s_setprio 1
	v_mfma_f32_16x16x32_bf16 v[66:69], v[212:215], v[18:21], v[110:113]
	v_mfma_f32_16x16x32_bf16 v[18:21], v[220:223], v[18:21], v[34:37]
	v_mfma_f32_16x16x32_bf16 v[122:125], v[224:227], v[22:25], v[18:21]
	v_mfma_f32_16x16x32_bf16 v[18:21], v[212:215], v[228:231], v[38:41]
	v_mfma_f32_16x16x32_bf16 v[110:113], v[216:219], v[232:235], v[18:21]
	v_mfma_f32_16x16x32_bf16 v[18:21], v[220:223], v[228:231], v[42:45]
	v_mfma_f32_16x16x32_bf16 v[106:109], v[224:227], v[232:235], v[18:21]
	v_mfma_f32_16x16x32_bf16 v[18:21], v[212:215], v[236:239], v[46:49]
	v_mfma_f32_16x16x32_bf16 v[94:97], v[216:219], v[240:243], v[18:21]
	v_mfma_f32_16x16x32_bf16 v[18:21], v[220:223], v[236:239], v[50:53]
	v_mfma_f32_16x16x32_bf16 v[90:93], v[224:227], v[240:243], v[18:21]
	v_mfma_f32_16x16x32_bf16 v[18:21], v[212:215], v[244:247], v[54:57]
	v_mfma_f32_16x16x32_bf16 v[78:81], v[216:219], v[248:251], v[18:21]
	v_mfma_f32_16x16x32_bf16 v[18:21], v[220:223], v[244:247], v[58:61]
	v_mfma_f32_16x16x32_bf16 v[126:129], v[216:219], v[22:25], v[66:69]
	v_mfma_f32_16x16x32_bf16 v[74:77], v[224:227], v[248:251], v[18:21]
	s_setprio 0
	s_barrier
	s_add_i32 s3, s3, s51
	s_nop 2
	v_lshl_add_u64 v[18:19], v[184:185], 0, s[78:79]
	s_mov_b32 m0, s3
	s_add_i32 s34, s3, 0x2000
	ds_read_b128 v[42:45], v147 offset:49152
	ds_read_b128 v[46:49], v147 offset:50176
	ds_read_b128 v[228:231], v147 offset:51200
	ds_read_b128 v[232:235], v147 offset:52224
	ds_read_b128 v[236:239], v147 offset:53248
	ds_read_b128 v[240:243], v147 offset:54272
	ds_read_b128 v[244:247], v147 offset:55296
	ds_read_b128 v[248:251], v147 offset:56320
	global_load_lds_dwordx4 v[18:19], off
	v_lshl_add_u64 v[18:19], v[184:185], 0, s[82:83]
	s_mov_b32 m0, s34
	s_add_i32 s35, s35, s51
	global_load_lds_dwordx4 v[18:19], off
	v_lshl_add_u64 v[18:19], v[184:185], 0, s[84:85]
	s_mov_b32 m0, s35
	s_add_i32 s36, s35, 0x2000
	global_load_lds_dwordx4 v[18:19], off
	v_lshl_add_u64 v[18:19], v[184:185], 0, s[86:87]
	s_mov_b32 m0, s36
	s_nop 0
	global_load_lds_dwordx4 v[18:19], off
	v_lshl_add_u64 v[18:19], v[140:141], 0, s[78:79]
	s_mov_b32 m0, s57
	s_nop 0
	global_load_lds_dwordx4 v[18:19], off
	v_lshl_add_u64 v[18:19], v[140:141], 0, s[82:83]
	s_mov_b32 m0, s58
	s_nop 0
	global_load_lds_dwordx4 v[18:19], off
	s_waitcnt vmcnt(8)
	s_waitcnt lgkmcnt(0)
	s_waitcnt lgkmcnt(0)
	v_mfma_f32_16x16x32_bf16 v[18:21], v[6:9], v[42:45], v[152:155]
	v_mfma_f32_16x16x32_bf16 v[54:57], v[26:29], v[46:49], v[18:21]
	s_barrier
	s_setprio 1
	v_mfma_f32_16x16x32_bf16 v[18:21], v[30:33], v[42:45], v[156:159]
	v_mfma_f32_16x16x32_bf16 v[50:53], v[208:211], v[46:49], v[18:21]
	v_mfma_f32_16x16x32_bf16 v[18:21], v[6:9], v[228:231], v[160:163]
	v_mfma_f32_16x16x32_bf16 v[38:41], v[26:29], v[232:235], v[18:21]
	v_mfma_f32_16x16x32_bf16 v[18:21], v[30:33], v[228:231], v[164:167]
	v_mfma_f32_16x16x32_bf16 v[34:37], v[208:211], v[232:235], v[18:21]
	v_mfma_f32_16x16x32_bf16 v[18:21], v[6:9], v[236:239], v[168:171]
	v_mfma_f32_16x16x32_bf16 v[2:5], v[6:9], v[244:247], v[2:5]
	v_mfma_f32_16x16x32_bf16 v[22:25], v[26:29], v[240:243], v[18:21]
	v_mfma_f32_16x16x32_bf16 v[18:21], v[30:33], v[236:239], v[172:175]
	v_mfma_f32_16x16x32_bf16 v[6:9], v[26:29], v[248:251], v[2:5]
	v_mfma_f32_16x16x32_bf16 v[2:5], v[30:33], v[244:247], v[10:13]
	v_mfma_f32_16x16x32_bf16 v[18:21], v[208:211], v[240:243], v[18:21]
	v_mfma_f32_16x16x32_bf16 v[2:5], v[208:211], v[248:251], v[2:5]
	s_setprio 0
	s_setprio 1
	v_mfma_f32_16x16x32_bf16 v[10:13], v[212:215], v[42:45], v[14:17]
	v_mfma_f32_16x16x32_bf16 v[66:69], v[216:219], v[46:49], v[10:13]
	v_mfma_f32_16x16x32_bf16 v[10:13], v[220:223], v[42:45], v[176:179]
	v_mfma_f32_16x16x32_bf16 v[58:61], v[224:227], v[46:49], v[10:13]
	v_mfma_f32_16x16x32_bf16 v[10:13], v[212:215], v[228:231], v[180:183]
	v_mfma_f32_16x16x32_bf16 v[46:49], v[216:219], v[232:235], v[10:13]
	v_mfma_f32_16x16x32_bf16 v[10:13], v[220:223], v[228:231], v[188:191]
	v_mfma_f32_16x16x32_bf16 v[42:45], v[224:227], v[232:235], v[10:13]
	v_mfma_f32_16x16x32_bf16 v[10:13], v[212:215], v[236:239], v[192:195]
	v_mfma_f32_16x16x32_bf16 v[30:33], v[216:219], v[240:243], v[10:13]
	v_mfma_f32_16x16x32_bf16 v[10:13], v[220:223], v[236:239], v[196:199]
	v_mfma_f32_16x16x32_bf16 v[26:29], v[224:227], v[240:243], v[10:13]
	v_mfma_f32_16x16x32_bf16 v[10:13], v[212:215], v[244:247], v[200:203]
	v_mfma_f32_16x16x32_bf16 v[14:17], v[216:219], v[248:251], v[10:13]
	v_mfma_f32_16x16x32_bf16 v[10:13], v[220:223], v[244:247], v[204:207]
	v_mfma_f32_16x16x32_bf16 v[10:13], v[224:227], v[248:251], v[10:13]
	s_setprio 0
	s_barrier
	v_lshl_add_u64 v[140:141], s[24:25], 0, v[134:135]
	s_mov_b32 s37, 0
	s_mov_b64 s[6:7], 0

.LBB0_1717:
	s_add_u32 s50, s6, 0x200
	s_addc_u32 s51, s7, 0
	s_ashr_i32 s73, s72, 31
	s_lshl_b64 s[12:13], s[72:73], 19
	s_add_u32 s78, s42, s12
	s_addc_u32 s79, s43, s13
	s_and_b64 s[12:13], s[0:1], exec
	s_cselect_b32 s73, s79, s15
	s_cselect_b32 s93, s78, s14
	s_ashr_i32 s67, s66, 31
	s_lshl_b64 s[12:13], s[66:67], 19
	v_readlane_b32 s18, v255, 15
	v_readlane_b32 s19, v255, 16
	s_add_u32 s74, s18, s12
	s_addc_u32 s75, s19, s13
	s_and_b64 s[12:13], s[0:1], exec
	s_cselect_b32 s67, s75, s7
	s_cselect_b32 s94, s74, s6
	s_and_b64 s[12:13], s[0:1], exec
	s_cselect_b32 s12, 0, 0x700
	s_add_u32 s93, s93, s12
	s_addc_u32 s73, s73, 0
	s_add_u32 s94, s94, s12
	s_addc_u32 s67, s67, 0
	v_lshl_add_u64 v[140:141], s[14:15], 0, v[130:131]
	s_add_i32 s95, s11, 0xc000
	v_lshl_add_u64 v[66:67], v[140:141], 0, s[38:39]
	s_mov_b32 m0, s95
	s_add_i32 s96, s11, 0xe000
	global_load_lds_dwordx4 v[66:67], off
	v_lshl_add_u64 v[66:67], v[140:141], 0, s[40:41]
	s_mov_b32 m0, s96
	s_nop 0
	global_load_lds_dwordx4 v[66:67], off
	s_waitcnt vmcnt(8)
	s_waitcnt lgkmcnt(0)
	s_waitcnt lgkmcnt(0)
	v_mfma_f32_16x16x32_bf16 v[86:89], v[10:13], v[50:53], 0
	v_mfma_f32_16x16x32_bf16 v[90:93], v[14:17], v[54:57], v[86:89]
	s_barrier
	s_setprio 1
	v_mfma_f32_16x16x32_bf16 v[86:89], v[2:5], v[58:61], 0
	v_mfma_f32_16x16x32_bf16 v[66:69], v[2:5], v[34:37], 0
	v_mfma_f32_16x16x32_bf16 v[70:73], v[10:13], v[34:37], 0
	v_mfma_f32_16x16x32_bf16 v[74:77], v[2:5], v[42:45], 0
	v_mfma_f32_16x16x32_bf16 v[78:81], v[10:13], v[42:45], 0
	v_mfma_f32_16x16x32_bf16 v[82:85], v[2:5], v[50:53], 0
	v_mfma_f32_16x16x32_bf16 v[94:97], v[6:9], v[62:65], v[86:89]
	v_mfma_f32_16x16x32_bf16 v[86:89], v[10:13], v[58:61], 0
	v_mfma_f32_16x16x32_bf16 v[66:69], v[6:9], v[38:41], v[66:69]
	v_mfma_f32_16x16x32_bf16 v[70:73], v[14:17], v[38:41], v[70:73]
	v_mfma_f32_16x16x32_bf16 v[74:77], v[6:9], v[46:49], v[74:77]
	v_mfma_f32_16x16x32_bf16 v[78:81], v[14:17], v[46:49], v[78:81]
	v_mfma_f32_16x16x32_bf16 v[82:85], v[6:9], v[54:57], v[82:85]
	v_mfma_f32_16x16x32_bf16 v[106:109], v[14:17], v[62:65], v[86:89]
	s_setprio 0
	s_setprio 1
	v_mfma_f32_16x16x32_bf16 v[86:89], v[18:21], v[34:37], 0
	v_mfma_f32_16x16x32_bf16 v[34:37], v[26:29], v[34:37], 0
	v_mfma_f32_16x16x32_bf16 v[110:113], v[22:25], v[38:41], v[86:89]
	v_mfma_f32_16x16x32_bf16 v[34:37], v[30:33], v[38:41], v[34:37]
	v_mfma_f32_16x16x32_bf16 v[38:41], v[18:21], v[42:45], 0
	v_mfma_f32_16x16x32_bf16 v[42:45], v[26:29], v[42:45], 0
	v_mfma_f32_16x16x32_bf16 v[38:41], v[22:25], v[46:49], v[38:41]
	v_mfma_f32_16x16x32_bf16 v[42:45], v[30:33], v[46:49], v[42:45]
	v_mfma_f32_16x16x32_bf16 v[46:49], v[18:21], v[50:53], 0
	v_mfma_f32_16x16x32_bf16 v[50:53], v[26:29], v[50:53], 0
	v_mfma_f32_16x16x32_bf16 v[46:49], v[22:25], v[54:57], v[46:49]
	v_mfma_f32_16x16x32_bf16 v[50:53], v[30:33], v[54:57], v[50:53]
	v_mfma_f32_16x16x32_bf16 v[54:57], v[18:21], v[58:61], 0
	v_mfma_f32_16x16x32_bf16 v[58:61], v[26:29], v[58:61], 0
	v_mfma_f32_16x16x32_bf16 v[54:57], v[22:25], v[62:65], v[54:57]
	v_mfma_f32_16x16x32_bf16 v[58:61], v[30:33], v[62:65], v[58:61]
	s_setprio 0
	s_barrier
	v_lshl_add_u64 v[184:185], s[6:7], 0, v[132:133]
	s_add_i32 s97, s89, s52
	v_lshl_add_u64 v[150:151], v[184:185], 0, s[46:47]
	s_mov_b32 m0, s97
	s_add_i32 vcc_lo, s97, 0x2000
	ds_read_b128 v[62:65], v147 offset:16384
	ds_read_b128 v[86:89], v147 offset:17408
	ds_read_b128 v[98:101], v147 offset:18432
	ds_read_b128 v[102:105], v147 offset:19456
	ds_read_b128 v[114:117], v147 offset:20480
	ds_read_b128 v[118:121], v147 offset:21504
	ds_read_b128 v[122:125], v147 offset:22528
	ds_read_b128 v[126:129], v147 offset:23552
	global_load_lds_dwordx4 v[150:151], off
	v_lshl_add_u64 v[150:151], v[184:185], 0, s[48:49]
	s_mov_b32 m0, vcc_lo
	s_add_i32 s33, s90, s52
	global_load_lds_dwordx4 v[150:151], off
	v_lshl_add_u64 v[150:151], v[184:185], 0, s[54:55]
	s_mov_b32 m0, s33
	s_add_i32 vcc_hi, s33, 0x2000
	global_load_lds_dwordx4 v[150:151], off
	v_lshl_add_u64 v[150:151], v[184:185], 0, s[56:57]
	s_mov_b32 m0, vcc_hi
	s_nop 0
	global_load_lds_dwordx4 v[150:151], off
	v_lshl_add_u64 v[150:151], v[140:141], 0, s[46:47]
	s_mov_b32 m0, s11
	s_nop 0
	global_load_lds_dwordx4 v[150:151], off
	v_lshl_add_u64 v[150:151], v[140:141], 0, s[48:49]
	s_mov_b32 m0, s77
	s_nop 0
	global_load_lds_dwordx4 v[150:151], off
	s_waitcnt vmcnt(8)
	s_waitcnt lgkmcnt(0)
	s_waitcnt lgkmcnt(0)
	v_mfma_f32_16x16x32_bf16 v[150:153], v[2:5], v[62:65], 0
	v_mfma_f32_16x16x32_bf16 v[160:163], v[2:5], v[98:101], 0
	s_barrier
	s_setprio 1
	v_mfma_f32_16x16x32_bf16 v[168:171], v[2:5], v[114:117], 0
	v_mfma_f32_16x16x32_bf16 v[2:5], v[2:5], v[122:125], 0
	v_mfma_f32_16x16x32_bf16 v[152:155], v[6:9], v[86:89], v[150:153]
	v_mfma_f32_16x16x32_bf16 v[160:163], v[6:9], v[102:105], v[160:163]
	v_mfma_f32_16x16x32_bf16 v[168:171], v[6:9], v[118:121], v[168:171]
	v_mfma_f32_16x16x32_bf16 v[2:5], v[6:9], v[126:129], v[2:5]
	v_mfma_f32_16x16x32_bf16 v[6:9], v[10:13], v[122:125], 0
	v_mfma_f32_16x16x32_bf16 v[156:159], v[10:13], v[62:65], 0
	v_mfma_f32_16x16x32_bf16 v[164:167], v[10:13], v[98:101], 0
	v_mfma_f32_16x16x32_bf16 v[172:175], v[10:13], v[114:117], 0
	v_mfma_f32_16x16x32_bf16 v[10:13], v[14:17], v[126:129], v[6:9]
	v_mfma_f32_16x16x32_bf16 v[156:159], v[14:17], v[86:89], v[156:159]
	v_mfma_f32_16x16x32_bf16 v[164:167], v[14:17], v[102:105], v[164:167]
	v_mfma_f32_16x16x32_bf16 v[172:175], v[14:17], v[118:121], v[172:175]
	s_setprio 0
	s_setprio 1
	v_mfma_f32_16x16x32_bf16 v[6:9], v[18:21], v[62:65], 0
	v_mfma_f32_16x16x32_bf16 v[14:17], v[22:25], v[86:89], v[6:9]
	v_mfma_f32_16x16x32_bf16 v[6:9], v[26:29], v[62:65], 0
	v_mfma_f32_16x16x32_bf16 v[176:179], v[30:33], v[86:89], v[6:9]
	v_mfma_f32_16x16x32_bf16 v[6:9], v[18:21], v[98:101], 0
	v_mfma_f32_16x16x32_bf16 v[180:183], v[22:25], v[102:105], v[6:9]
	v_mfma_f32_16x16x32_bf16 v[6:9], v[26:29], v[98:101], 0
	v_mfma_f32_16x16x32_bf16 v[188:191], v[30:33], v[102:105], v[6:9]
	v_mfma_f32_16x16x32_bf16 v[6:9], v[18:21], v[114:117], 0
	v_mfma_f32_16x16x32_bf16 v[192:195], v[22:25], v[118:121], v[6:9]
	v_mfma_f32_16x16x32_bf16 v[6:9], v[26:29], v[114:117], 0
	v_mfma_f32_16x16x32_bf16 v[196:199], v[30:33], v[118:121], v[6:9]
	v_mfma_f32_16x16x32_bf16 v[6:9], v[18:21], v[122:125], 0
	v_mfma_f32_16x16x32_bf16 v[200:203], v[22:25], v[126:129], v[6:9]
	v_mfma_f32_16x16x32_bf16 v[6:9], v[26:29], v[122:125], 0
	v_mfma_f32_16x16x32_bf16 v[204:207], v[30:33], v[126:129], v[6:9]
	s_setprio 0
	s_barrier
	s_add_i32 s12, 0, 0x18000
	s_add_i32 s3, 0, 0x1c000
	v_add_u32_e32 v149, s12, v144
	v_add_u32_e32 v150, s3, v144
	s_nop 0
	ds_read_b128 v[6:9], v149
	ds_read_b128 v[26:29], v149 offset:1024
	ds_read_b128 v[30:33], v149 offset:2048
	ds_read_b128 v[208:211], v149 offset:3072
	ds_read_b128 v[212:215], v150
	ds_read_b128 v[216:219], v150 offset:1024
	ds_read_b128 v[220:223], v150 offset:2048
	ds_read_b128 v[224:227], v150 offset:3072
	s_mov_b32 m0, s80
	v_lshl_add_u64 v[62:63], v[140:141], 0, s[54:55]
	ds_read_b128 v[18:21], v147 offset:32768
	ds_read_b128 v[22:25], v147 offset:33792
	ds_read_b128 v[228:231], v147 offset:34816
	ds_read_b128 v[232:235], v147 offset:35840
	ds_read_b128 v[236:239], v147 offset:36864
	ds_read_b128 v[240:243], v147 offset:37888
	ds_read_b128 v[244:247], v147 offset:38912
	ds_read_b128 v[248:251], v147 offset:39936
	global_load_lds_dwordx4 v[62:63], off
	v_lshl_add_u64 v[62:63], v[140:141], 0, s[56:57]
	s_mov_b32 m0, s81
	s_nop 0
	global_load_lds_dwordx4 v[62:63], off
	s_waitcnt vmcnt(8)
	s_waitcnt lgkmcnt(0)
	s_waitcnt lgkmcnt(0)
	v_mfma_f32_16x16x32_bf16 v[62:65], v[6:9], v[18:21], v[66:69]
	v_mfma_f32_16x16x32_bf16 v[118:121], v[26:29], v[22:25], v[62:65]
	s_barrier
	s_setprio 1
	v_mfma_f32_16x16x32_bf16 v[62:65], v[30:33], v[18:21], v[70:73]
	v_mfma_f32_16x16x32_bf16 v[114:117], v[208:211], v[22:25], v[62:65]
	v_mfma_f32_16x16x32_bf16 v[62:65], v[6:9], v[228:231], v[74:77]
	v_mfma_f32_16x16x32_bf16 v[102:105], v[26:29], v[232:235], v[62:65]
	v_mfma_f32_16x16x32_bf16 v[62:65], v[30:33], v[228:231], v[78:81]
	v_mfma_f32_16x16x32_bf16 v[98:101], v[208:211], v[232:235], v[62:65]
	v_mfma_f32_16x16x32_bf16 v[62:65], v[6:9], v[236:239], v[82:85]
	v_mfma_f32_16x16x32_bf16 v[86:89], v[26:29], v[240:243], v[62:65]
	v_mfma_f32_16x16x32_bf16 v[62:65], v[30:33], v[236:239], v[90:93]
	v_mfma_f32_16x16x32_bf16 v[82:85], v[208:211], v[240:243], v[62:65]
	v_mfma_f32_16x16x32_bf16 v[62:65], v[6:9], v[244:247], v[94:97]
	v_mfma_f32_16x16x32_bf16 v[70:73], v[26:29], v[248:251], v[62:65]
	v_mfma_f32_16x16x32_bf16 v[62:65], v[30:33], v[244:247], v[106:109]
	v_mfma_f32_16x16x32_bf16 v[62:65], v[208:211], v[248:251], v[62:65]
	s_setprio 0
	s_setprio 1
	v_mfma_f32_16x16x32_bf16 v[66:69], v[212:215], v[18:21], v[110:113]
	v_mfma_f32_16x16x32_bf16 v[18:21], v[220:223], v[18:21], v[34:37]
	v_mfma_f32_16x16x32_bf16 v[122:125], v[224:227], v[22:25], v[18:21]
	v_mfma_f32_16x16x32_bf16 v[18:21], v[212:215], v[228:231], v[38:41]
	v_mfma_f32_16x16x32_bf16 v[110:113], v[216:219], v[232:235], v[18:21]
	v_mfma_f32_16x16x32_bf16 v[18:21], v[220:223], v[228:231], v[42:45]
	v_mfma_f32_16x16x32_bf16 v[106:109], v[224:227], v[232:235], v[18:21]
	v_mfma_f32_16x16x32_bf16 v[18:21], v[212:215], v[236:239], v[46:49]
	v_mfma_f32_16x16x32_bf16 v[94:97], v[216:219], v[240:243], v[18:21]
	v_mfma_f32_16x16x32_bf16 v[18:21], v[220:223], v[236:239], v[50:53]
	v_mfma_f32_16x16x32_bf16 v[90:93], v[224:227], v[240:243], v[18:21]
	v_mfma_f32_16x16x32_bf16 v[18:21], v[212:215], v[244:247], v[54:57]
	v_mfma_f32_16x16x32_bf16 v[78:81], v[216:219], v[248:251], v[18:21]
	v_mfma_f32_16x16x32_bf16 v[18:21], v[220:223], v[244:247], v[58:61]
	v_mfma_f32_16x16x32_bf16 v[126:129], v[216:219], v[22:25], v[66:69]
	v_mfma_f32_16x16x32_bf16 v[74:77], v[224:227], v[248:251], v[18:21]
	s_setprio 0
	s_barrier
	s_add_i32 s12, s12, s52
	s_nop 2
	v_lshl_add_u64 v[18:19], v[184:185], 0, s[58:59]
	s_mov_b32 m0, s12
	s_add_i32 s13, s12, 0x2000
	ds_read_b128 v[42:45], v147 offset:49152
	ds_read_b128 v[46:49], v147 offset:50176
	ds_read_b128 v[228:231], v147 offset:51200
	ds_read_b128 v[232:235], v147 offset:52224
	ds_read_b128 v[236:239], v147 offset:53248
	ds_read_b128 v[240:243], v147 offset:54272
	ds_read_b128 v[244:247], v147 offset:55296
	ds_read_b128 v[248:251], v147 offset:56320
	global_load_lds_dwordx4 v[18:19], off
	v_lshl_add_u64 v[18:19], v[184:185], 0, s[60:61]
	s_mov_b32 m0, s13
	s_add_i32 s3, s3, s52
	global_load_lds_dwordx4 v[18:19], off
	v_lshl_add_u64 v[18:19], v[184:185], 0, s[62:63]
	s_mov_b32 m0, s3
	s_add_i32 s36, s3, 0x2000
	global_load_lds_dwordx4 v[18:19], off
	v_lshl_add_u64 v[18:19], v[184:185], 0, s[64:65]
	s_mov_b32 m0, s36
	s_nop 0
	global_load_lds_dwordx4 v[18:19], off
	v_lshl_add_u64 v[18:19], v[140:141], 0, s[58:59]
	s_mov_b32 m0, s86
	s_nop 0
	global_load_lds_dwordx4 v[18:19], off
	v_lshl_add_u64 v[18:19], v[140:141], 0, s[60:61]
	s_mov_b32 m0, s87
	s_nop 0
	global_load_lds_dwordx4 v[18:19], off
	s_waitcnt vmcnt(8)
	s_waitcnt lgkmcnt(0)
	s_waitcnt lgkmcnt(0)
	v_mfma_f32_16x16x32_bf16 v[18:21], v[6:9], v[42:45], v[152:155]
	v_mfma_f32_16x16x32_bf16 v[54:57], v[26:29], v[46:49], v[18:21]
	s_barrier
	s_setprio 1
	v_mfma_f32_16x16x32_bf16 v[18:21], v[30:33], v[42:45], v[156:159]
	v_mfma_f32_16x16x32_bf16 v[50:53], v[208:211], v[46:49], v[18:21]
	v_mfma_f32_16x16x32_bf16 v[18:21], v[6:9], v[228:231], v[160:163]
	v_mfma_f32_16x16x32_bf16 v[38:41], v[26:29], v[232:235], v[18:21]
	v_mfma_f32_16x16x32_bf16 v[18:21], v[30:33], v[228:231], v[164:167]
	v_mfma_f32_16x16x32_bf16 v[34:37], v[208:211], v[232:235], v[18:21]
	v_mfma_f32_16x16x32_bf16 v[18:21], v[6:9], v[236:239], v[168:171]
	v_mfma_f32_16x16x32_bf16 v[2:5], v[6:9], v[244:247], v[2:5]
	v_mfma_f32_16x16x32_bf16 v[22:25], v[26:29], v[240:243], v[18:21]
	v_mfma_f32_16x16x32_bf16 v[18:21], v[30:33], v[236:239], v[172:175]
	v_mfma_f32_16x16x32_bf16 v[6:9], v[26:29], v[248:251], v[2:5]
	v_mfma_f32_16x16x32_bf16 v[2:5], v[30:33], v[244:247], v[10:13]
	v_mfma_f32_16x16x32_bf16 v[18:21], v[208:211], v[240:243], v[18:21]
	v_mfma_f32_16x16x32_bf16 v[2:5], v[208:211], v[248:251], v[2:5]
	s_setprio 0
	s_setprio 1
	v_mfma_f32_16x16x32_bf16 v[10:13], v[212:215], v[42:45], v[14:17]
	v_mfma_f32_16x16x32_bf16 v[66:69], v[216:219], v[46:49], v[10:13]
	v_mfma_f32_16x16x32_bf16 v[10:13], v[220:223], v[42:45], v[176:179]
	v_mfma_f32_16x16x32_bf16 v[58:61], v[224:227], v[46:49], v[10:13]
	v_mfma_f32_16x16x32_bf16 v[10:13], v[212:215], v[228:231], v[180:183]
	v_mfma_f32_16x16x32_bf16 v[46:49], v[216:219], v[232:235], v[10:13]
	v_mfma_f32_16x16x32_bf16 v[10:13], v[220:223], v[228:231], v[188:191]
	v_mfma_f32_16x16x32_bf16 v[42:45], v[224:227], v[232:235], v[10:13]
	v_mfma_f32_16x16x32_bf16 v[10:13], v[212:215], v[236:239], v[192:195]
	v_mfma_f32_16x16x32_bf16 v[30:33], v[216:219], v[240:243], v[10:13]
	v_mfma_f32_16x16x32_bf16 v[10:13], v[220:223], v[236:239], v[196:199]
	v_mfma_f32_16x16x32_bf16 v[26:29], v[224:227], v[240:243], v[10:13]
	v_mfma_f32_16x16x32_bf16 v[10:13], v[212:215], v[244:247], v[200:203]
	v_mfma_f32_16x16x32_bf16 v[14:17], v[216:219], v[248:251], v[10:13]
	v_mfma_f32_16x16x32_bf16 v[10:13], v[220:223], v[244:247], v[204:207]
	v_mfma_f32_16x16x32_bf16 v[10:13], v[224:227], v[248:251], v[10:13]
	s_setprio 0
	s_barrier
	v_lshl_add_u64 v[140:141], s[14:15], 0, v[134:135]
	s_mov_b32 s37, 0
	s_mov_b64 s[6:7], 0
